# next-phase prefetch in barrier slack: waves 1-7 touch the first two K-tiles of the next phase's weight tile (P5, P6) and P5's gate-code tiles before the grid barrier releases
# baseline (speedup 1.0000x reference)
.LBB0_517:
	v_readlane_b32 s0, v254, 38
	s_or_b32 s2, s0, 5
	v_readlane_b32 s0, v252, 6
	v_readlane_b32 s1, v252, 7
	s_cmp_lt_i32 s2, s1
	s_cselect_b64 s[0:1], -1, 0
	s_and_b64 s[4:5], s[20:21], s[0:1]
	s_andn2_b64 vcc, exec, s[4:5]
	s_cbranch_vccnz .LBB0_567
	s_waitcnt vmcnt(0)
	s_barrier
	s_mov_b64 s[10:11], exec
	v_readlane_b32 s4, v252, 4
	v_readlane_b32 s5, v252, 5
	s_and_b64 s[4:5], s[10:11], s[4:5]
	s_mov_b64 exec, s[4:5]
	s_cbranch_execz .Lseam_pf5
	s_branch .Lseam_lead5
.Lseam_pf5:
	s_mov_b64 exec, s[10:11]
	v_readlane_b32 s78, v254, 20
	v_mov_b32_e32 v2, s78
	ds_read_b64 v[2:3], v2
	v_mbcnt_lo_u32_b32 v4, -1, 0
	v_mbcnt_hi_u32_b32 v4, -1, v4
	v_readlane_b32 s79, v252, 2
	v_readlane_b32 s82, v252, 8
	v_readlane_b32 s83, v254, 36
	s_waitcnt lgkmcnt(0)
	v_readfirstlane_b32 s80, v2
	v_readfirstlane_b32 s81, v3
	s_and_b32 s84, s79, 1
	s_lshl_b32 s84, s84, 2
	s_lshr_b32 s85, s79, 6
	s_add_i32 s84, s84, s85
	s_lshr_b32 s82, s82, 6
	s_add_i32 s82, s82, -1
	s_lshl_b32 s85, s82, 10
	s_mov_b32 m0, s85
	s_mul_i32 s86, s83, 0xc00000
	s_mul_i32 s87, s84, 0x180000
	s_add_u32 s86, s86, s87
	s_add_u32 s86, s86, 0x76e00000
	s_add_u32 s86, s80, s86
	s_addc_u32 s87, s81, 0
	v_lshrrev_b32_e32 v5, 1, v4
	v_lshl_add_u32 v5, s82, 5, v5
	v_mul_u32_u24_e32 v5, 0x1800, v5
	v_and_b32_e32 v6, 1, v4
	v_lshl_add_u32 v5, v6, 7, v5
	global_load_lds_dword v5, s[86:87]
	s_and_b32 s86, s79, 7
	s_lshr_b32 s86, s86, 1
	s_lshl_b32 s86, s86, 3
	s_bfe_u32 s87, s79, 0x30003
	s_add_i32 s86, s86, s87
	s_lshl_b32 s86, s86, 17
	s_add_i32 s87, s84, 60
	s_lshl_b32 s87, s87, 22
	s_add_u32 s86, s86, s87
	s_add_u32 s86, s86, 0x36d00000
	s_add_u32 s86, s80, s86
	s_addc_u32 s87, s81, 0
	v_lshlrev_b32_e32 v5, 7, v4
	s_lshl_b32 s85, s82, 1
	s_add_i32 s85, s85, 0
	s_lshr_b32 s79, s85, 3
	s_lshl_b32 s79, s79, 25
	s_and_b32 s85, s85, 7
	s_lshl_b32 s85, s85, 13
	s_add_i32 s85, s85, s79
	v_add_u32_e32 v6, s85, v5
	global_load_lds_dword v6, s[86:87]
	s_lshl_b32 s85, s82, 1
	s_add_i32 s85, s85, 1
	s_lshr_b32 s79, s85, 3
	s_lshl_b32 s79, s79, 25
	s_and_b32 s85, s85, 7
	s_lshl_b32 s85, s85, 13
	s_add_i32 s85, s85, s79
	v_add_u32_e32 v6, s85, v5
	global_load_lds_dword v6, s[86:87]
	s_branch .LBB0_566
.Lseam_lead5:
	v_readlane_b32 s4, v252, 3
	s_waitcnt vmcnt(0) expcnt(0) lgkmcnt(0)
	s_nop 0
	v_mov_b32_e32 v0, s4
	ds_read_b32 v3, v0
	ds_read_b32 v2, v0 offset:4
	s_waitcnt lgkmcnt(1)
	v_cmp_ne_u32_e32 vcc, 0, v3
	s_cbranch_vccnz .LBB0_534
	v_readlane_b32 s6, v252, 0
	v_readlane_b32 s7, v252, 1
	s_load_dwordx2 s[4:5], s[6:7], 0x4
	s_waitcnt lgkmcnt(0)
	s_mul_i32 s4, s4, s56
	s_mul_i32 s4, s4, s5
	s_mov_b32 s5, 1
	s_branch .LBB0_522

.LBB0_594:
	v_readlane_b32 s0, v254, 38
	s_or_b32 s2, s0, 6
	v_readlane_b32 s0, v252, 6
	v_readlane_b32 s1, v252, 7
	s_cmp_lt_i32 s2, s1
	s_cselect_b64 s[0:1], -1, 0
	s_and_b64 s[4:5], s[10:11], s[0:1]
	s_andn2_b64 vcc, exec, s[4:5]
	s_cbranch_vccnz .LBB0_644
	s_waitcnt vmcnt(0)
	s_barrier
	s_mov_b64 s[10:11], exec
	v_readlane_b32 s4, v252, 4
	v_readlane_b32 s5, v252, 5
	s_and_b64 s[4:5], s[10:11], s[4:5]
	s_mov_b64 exec, s[4:5]
	s_cbranch_execz .Lseam_pf6
	s_branch .Lseam_lead6
.Lseam_pf6:
	s_mov_b64 exec, s[10:11]
	v_readlane_b32 s78, v254, 20
	v_mov_b32_e32 v2, s78
	ds_read_b64 v[2:3], v2
	v_mbcnt_lo_u32_b32 v4, -1, 0
	v_mbcnt_hi_u32_b32 v4, -1, v4
	v_readlane_b32 s79, v252, 2
	v_readlane_b32 s82, v252, 8
	v_readlane_b32 s83, v254, 36
	s_waitcnt lgkmcnt(0)
	v_readfirstlane_b32 s80, v2
	v_readfirstlane_b32 s81, v3
	s_and_b32 s84, s79, 1
	s_lshl_b32 s84, s84, 2
	s_lshr_b32 s85, s79, 6
	s_add_i32 s84, s84, s85
	s_lshr_b32 s82, s82, 6
	s_add_i32 s82, s82, -1
	s_lshl_b32 s85, s82, 10
	s_mov_b32 m0, s85
	s_mul_i32 s86, s83, 0x800000
	s_mul_i32 s87, s84, 0x100000
	s_add_u32 s86, s86, s87
	s_add_u32 s86, s86, 0x16500000
	s_add_u32 s86, s80, s86
	s_addc_u32 s87, s81, 0
	v_lshrrev_b32_e32 v5, 1, v4
	v_lshl_add_u32 v5, s82, 5, v5
	v_mul_u32_u24_e32 v5, 0x1000, v5
	v_and_b32_e32 v6, 1, v4
	v_lshl_add_u32 v5, v6, 7, v5
	global_load_lds_dword v5, s[86:87]
	s_branch .LBB0_643
